# bundle: attention row-sum tail as packed tree adds, pass3 q load hoisted, GLA cum scan LDS reads batched
# speedup vs baseline: 1.0054x; 1.0054x over previous
.LBB0_734:
	s_abs_i32 s1, s74
	v_readlane_b32 s2, v255, 40
	s_mul_hi_u32 s2, s1, s2
	s_mul_i32 s3, s2, s41
	s_sub_i32 s1, s1, s3
	s_ashr_i32 s0, s74, 31
	s_add_i32 s3, s2, 1
	s_sub_i32 s8, s1, s41
	s_cmp_ge_u32 s1, s41
	s_cselect_b32 s2, s3, s2
	s_cselect_b32 s1, s8, s1
	s_add_i32 s3, s2, 1
	s_cmp_ge_u32 s1, s41
	s_cselect_b32 s1, s3, s2
	s_xor_b32 s1, s1, s0
	s_sub_i32 s1, s1, s0
	s_and_b32 s0, s1, 3
	s_ashr_i32 s1, s1, 2
	s_sub_i32 s75, 1, s1
	s_lshl_b32 s2, s21, 6
	v_mov_b32_e32 v10, v207
	s_cmp_lt_i32 s21, 4
	s_cselect_b32 s22, s7, s6
	v_lshlrev_b32_e32 v0, 4, v10
	v_and_b32_e32 v66, 0x70, v0
	s_add_i32 s22, s22, s2
	v_mov_b32_e32 v0, v207
	s_barrier
	s_cmp_lg_u32 s1, 1
	v_and_b32_e32 v6, 63, v0
	v_or_b32_e32 v1, s22, v6
	s_movk_i32 s2, 0x1200
	s_cselect_b64 s[96:97], -1, 0
	s_lshl_b32 s20, s0, 7
	s_lshl_b32 s26, s0, 8
	v_mul_lo_u32 v128, v1, s2
	s_cmp_eq_u32 s1, 1
	s_movk_i32 s1, 0x800
	v_ashrrev_i32_e32 v0, 2, v0
	v_lshl_add_u64 v[2:3], v[128:129], 1, s[36:37]
	s_cselect_b32 s94, s1, 0x1c00
	s_mov_b32 s95, 0
	v_and_b32_e32 v0, -16, v0
	v_lshl_add_u64 v[2:3], v[2:3], 0, s[94:95]
	v_lshl_add_u64 v[2:3], v[2:3], 0, s[26:27]
	v_ashrrev_i32_e32 v1, 31, v0
	v_lshl_add_u64 v[4:5], v[0:1], 1, v[2:3]
	s_movk_i32 s8, 0x90
	v_lshlrev_b32_e32 v12, 1, v6
	v_mul_lo_u32 v13, v0, s8
	global_load_dwordx4 v[0:3], v[4:5], off
	s_nop 0
	global_load_dwordx4 v[4:7], v[4:5], off offset:16
	v_ashrrev_i32_e32 v67, 3, v10
	v_mov_b64_e32 v[8:9], s[36:37]
	v_readlane_b32 s4, v252, 12
	v_add_u32_e32 v64, s22, v67
	v_mad_i64_i32 v[68:69], s[2:3], v64, s14, v[8:9]
	v_add3_u32 v14, s4, v12, v13
	v_add3_u32 v12, s4, v13, v12
	s_cselect_b32 s94, 0, 0x1000
	v_lshlrev_b32_e32 v128, 1, v66
	v_ashrrev_i32_e32 v11, 6, v10
	v_and_b32_e32 v92, 31, v10
	v_and_b32_e32 v94, 3, v11
	s_lshl_b32 s1, s75, 3
	s_lshl_b32 s2, s0, 1
	s_or_b32 s23, s1, s2
	v_bfe_u32 v93, v10, 5, 1
	s_cmp_gt_i32 s21, 3
	s_cselect_b32 s1, 0x87, 3
	v_lshl_add_u32 v95, v66, 2, 0
	v_readlane_b32 s5, v255, 1
	v_bfi_b32 v8, -16, v67, v10
	v_cvt_f32_ubyte0_e32 v96, s0
	v_ashrrev_i32_e32 v65, 31, v64
	s_mov_b64 s[92:93], -1
	v_lshl_add_u64 v[162:163], v[68:69], 0, s[94:95]
	v_lshl_add_u64 v[162:163], v[162:163], 0, s[26:27]
	v_lshl_add_u64 v[162:163], v[162:163], 0, v[128:129]
	global_load_dwordx4 v[154:157], v[162:163], off
	global_load_dwordx4 v[158:161], v[162:163], off offset:16
	s_waitcnt vmcnt(0) lgkmcnt(0)
	ds_write_b16 v14, v0
	ds_write_b16_d16_hi v12, v0 offset:144
	ds_write_b16 v14, v1 offset:288
	ds_write_b16_d16_hi v12, v1 offset:432
	ds_write_b16 v14, v2 offset:576
	ds_write_b16_d16_hi v12, v2 offset:720
	ds_write_b16 v14, v3 offset:864
	ds_write_b16_d16_hi v12, v3 offset:1008
	ds_write_b16 v14, v4 offset:1152
	ds_write_b16_d16_hi v12, v4 offset:1296
	ds_write_b16 v14, v5 offset:1440
	ds_write_b16_d16_hi v12, v5 offset:1584
	ds_write_b16 v14, v6 offset:1728
	ds_write_b16_d16_hi v12, v6 offset:1872
	ds_write_b16 v14, v7 offset:2016
	ds_write_b16_d16_hi v12, v7 offset:2160
	v_lshl_add_u64 v[0:1], v[68:69], 0, s[94:95]
	v_lshl_add_u64 v[0:1], v[0:1], 0, s[26:27]
	v_lshl_add_u64 v[4:5], v[0:1], 0, v[128:129]
	s_sub_i32 s94, s1, s21
	v_readlane_b32 s1, v255, 0
	s_add_u32 s2, s36, s26
	s_addc_u32 s3, s37, 0
	s_waitcnt vmcnt(0) lgkmcnt(0)
	v_lshlrev_b32_e32 v70, 16, v154
	v_lshlrev_b32_e32 v78, 16, v158
	v_and_b32_e32 v79, 0xffff0000, v158
	v_lshl_or_b32 v4, v94, 5, v92
	v_and_b32_e32 v71, 0xffff0000, v154
	v_lshlrev_b32_e32 v72, 16, v155
	v_and_b32_e32 v73, 0xffff0000, v155
	v_lshlrev_b32_e32 v0, 8, v4
	v_mov_b32_e32 v1, v129
	v_lshlrev_b32_e32 v74, 16, v156
	v_and_b32_e32 v75, 0xffff0000, v156
	v_lshlrev_b32_e32 v76, 16, v157
	v_and_b32_e32 v77, 0xffff0000, v157
	v_lshl_add_u64 v[0:1], s[84:85], 0, v[0:1]
	v_lshlrev_b32_e32 v2, 4, v93
	v_mov_b32_e32 v3, v129
	v_lshl_add_u64 v[86:87], v[0:1], 0, v[2:3]
	v_add_u32_e32 v3, s4, v2
	s_movk_i32 s4, 0x110
	v_lshlrev_b32_e32 v80, 16, v159
	v_and_b32_e32 v81, 0xffff0000, v159
	v_sub_u32_e32 v0, v95, v128
	v_add_u32_e32 v1, s5, v2
	v_add_u32_e32 v5, s1, v2
	v_mul_lo_u32 v2, v67, s4
	v_add_u32_e32 v97, v0, v2
	v_add3_u32 v98, s1, v128, v2
	v_and_b32_e32 v2, 48, v10
	v_add_u32_e32 v2, 0, v2
	v_mad_u64_u32 v[88:89], s[0:1], v8, s4, v[2:3]
	v_lshrrev_b32_e32 v8, 2, v10
	v_and_b32_e32 v8, 12, v8
	v_lshlrev_b32_e32 v84, 16, v161
	v_and_b32_e32 v85, 0xffff0000, v161
	v_lshlrev_b32_e32 v0, 5, v11
	v_and_b32_e32 v7, 15, v10
	v_and_or_b32 v8, v67, -16, v8
	v_and_or_b32 v0, v0, 32, v7
	v_or_b32_e32 v13, 1, v8
	v_or_b32_e32 v14, 2, v8
	v_or_b32_e32 v15, 3, v8
	s_movk_i32 s0, 0xffe0
	v_mul_u32_u24_e32 v7, 0x110, v0
	v_lshl_add_u32 v11, v0, 1, s5
	v_cmp_ge_i32_e64 s[42:43], v0, v8
	v_cmp_le_i32_e64 s[44:45], v0, v8
	v_cmp_gt_i32_e64 s[46:47], v0, v8
	v_cmp_le_i32_e64 s[48:49], v0, v13
	v_cmp_ge_i32_e64 s[50:51], v0, v14
	v_cmp_le_i32_e64 s[52:53], v0, v14
	v_cmp_ge_i32_e64 s[54:55], v0, v15
	v_cmp_le_i32_e64 s[56:57], v0, v15
	v_or_b32_e32 v0, 16, v0
	v_bfi_b32 v9, s0, v67, v10
	v_mul_lo_u32 v12, v8, s8
	v_lshlrev_b32_e32 v16, 1, v0
	v_lshlrev_b32_e32 v82, 16, v160
	v_and_b32_e32 v83, 0xffff0000, v160
	v_lshlrev_b32_e32 v6, 9, v67
	v_mul_lo_u32 v10, v9, s8
	v_mul_u32_u24_e32 v4, 0x90, v4
	v_mul_lo_u32 v9, v9, s4
	v_cmp_ge_i32_e64 s[58:59], v0, v8
	v_cmp_le_i32_e64 s[60:61], v0, v8
	v_add3_u32 v99, s5, v12, v16
	v_cmp_gt_i32_e64 s[62:63], v0, v8
	v_cmp_le_i32_e64 s[64:65], v0, v13
	v_cmp_ge_i32_e64 s[66:67], v0, v14
	v_cmp_le_i32_e64 s[68:69], v0, v14
	v_cmp_ge_i32_e64 s[70:71], v0, v15
	v_cmp_le_i32_e64 s[72:73], v0, v15
	v_mov_b32_e32 v0, 0
	v_and_b32_e32 v89, 0xffffffe0, v67
	v_add_u32_e32 v100, 0x90, v99
	v_add_u32_e32 v101, 0x120, v99
	v_add_u32_e32 v102, 0x1b0, v99
	v_add_u32_e32 v103, v95, v6
	v_add_u32_e32 v104, v2, v7
	v_add_u32_e32 v105, v11, v12
	v_add_u32_e32 v106, v1, v10
	v_add_u32_e32 v107, v3, v4
	v_add_u32_e32 v108, v5, v9
	v_mov_b32_e32 v1, v0
	v_mov_b32_e32 v2, v0
	v_mov_b32_e32 v3, v0
	v_mov_b32_e32 v4, v0
	v_mov_b32_e32 v5, v0
	v_mov_b32_e32 v6, v0
	v_mov_b32_e32 v7, v0
	v_mov_b32_e32 v8, v0
	v_mov_b32_e32 v9, v0
	v_mov_b32_e32 v10, v0
	v_mov_b32_e32 v11, v0
	v_mov_b32_e32 v12, v0
	v_mov_b32_e32 v13, v0
	v_mov_b32_e32 v14, v0
	v_mov_b32_e32 v15, v0
	s_branch .LBB0_736

.LBB0_1899:
	s_or_b64 exec, exec, s[2:3]
	v_pk_add_f32 v[80:81], v[96:97], v[80:81]
	v_pk_add_f32 v[64:65], v[64:65], v[112:113]
	v_add_f32_e32 v82, v98, v82
	v_add_f32_e32 v83, v246, v83
	v_pk_add_f32 v[66:67], v[66:67], v[114:115]
	v_pk_add_f32 v[84:85], v[100:101], v[84:85]
	v_pk_add_f32 v[68:69], v[68:69], v[116:117]
	v_pk_add_f32 v[86:87], v[102:103], v[86:87]
	v_pk_add_f32 v[70:71], v[70:71], v[118:119]
	v_pk_add_f32 v[88:89], v[104:105], v[88:89]
	v_pk_add_f32 v[72:73], v[72:73], v[120:121]
	v_pk_add_f32 v[90:91], v[106:107], v[90:91]
	v_pk_add_f32 v[74:75], v[74:75], v[122:123]
	v_pk_add_f32 v[92:93], v[108:109], v[92:93]
	v_pk_add_f32 v[76:77], v[76:77], v[124:125]
	v_pk_add_f32 v[94:95], v[110:111], v[94:95]
	v_add_f32_e32 v78, v78, v126
	v_add_f32_e32 v79, v79, v99
	v_pk_add_f32 v[80:81], v[80:81], v[82:83]
	v_pk_add_f32 v[64:65], v[64:65], v[66:67]
	v_pk_add_f32 v[84:85], v[84:85], v[86:87]
	v_pk_add_f32 v[68:69], v[68:69], v[70:71]
	v_pk_add_f32 v[88:89], v[88:89], v[90:91]
	v_pk_add_f32 v[72:73], v[72:73], v[74:75]
	v_pk_add_f32 v[92:93], v[92:93], v[94:95]
	v_pk_add_f32 v[76:77], v[76:77], v[78:79]
	v_pk_add_f32 v[80:81], v[80:81], v[84:85]
	v_pk_add_f32 v[64:65], v[64:65], v[68:69]
	v_pk_add_f32 v[88:89], v[88:89], v[92:93]
	v_pk_add_f32 v[72:73], v[72:73], v[76:77]
	v_pk_add_f32 v[80:81], v[80:81], v[88:89]
	v_pk_add_f32 v[64:65], v[64:65], v[72:73]
	v_add_f32_e32 v80, v80, v81
	v_add_f32_e32 v64, v64, v65
	s_add_i32 s8, s8, 1
	v_add_f32_e32 v131, v131, v80
	v_add_f32_e32 v193, v193, v64
	v_add3_u32 v64, s9, v244, v128
	v_lshl_add_u64 v[212:213], v[212:213], 0, s[24:25]
	v_lshl_add_u64 v[214:215], v[214:215], 0, s[16:17]
	s_cmpk_eq_i32 s8, 0x84
	v_lshl_add_u64 v[216:217], v[216:217], 0, s[16:17]
	ds_write_b128 v64, v[188:191] offset:13312
	s_waitcnt lgkmcnt(0)
	s_barrier
	s_cbranch_scc1 .LBB0_1908
